# P3 gate scales: mid-K RT block waits per load at its first consumer (counted vmcnt instead of vmcnt(0)), final G1 block issues all 16 loads before its first wait; on top of the de-serialised P2 prolog
# baseline (speedup 1.0000x reference)
;     __device__ __forceinline__ void scale(f32x4 (&acc)[2][2][4][2], const bf16_t* G, const Unit& u, int wr, int wc, int fr, int fq) const {
;         u32x4 gv[2][4][2];
; #pragma unroll
;         for (int ai = 0; ai < 2; ++ai)
; #pragma unroll
;             for (int m = 0; m < 4; ++m) { const size_t row = (size_t)u.pm * 256 + 128 * ai + 64 * wr + 16 * m + fr;
; #pragma unroll
;                 for (int bj = 0; bj < 2; ++bj) gv[ai][m][bj] = __builtin_nontemporal_load((const u32x4*)(G + row * DM + u.pn * 256 + 128 * bj + 32 * wc + 8 * fq)); }
; #pragma unroll
;         for (int ai = 0; ai < 2; ++ai)
; #pragma unroll
;             for (int m = 0; m < 4; ++m)
; #pragma unroll
;                 for (int bj = 0; bj < 2; ++bj) { const u32x4 a = gv[ai][m][bj];
;                     acc[ai][bj][m][0] *= (f32x4){bflo(a.x), bfhi(a.x), bflo(a.y), bfhi(a.y)}; acc[ai][bj][m][1] *= (f32x4){bflo(a.z), bfhi(a.z), bflo(a.w), bfhi(a.w)}; }
;     __device__ __forceinline__ void mid(f32x4 (&acc)[2][2][4][2], const Unit& u, int wr, int wc, int fr, int fq) const {
;     ...
;         scale(acc, RT, u, wr, wc, fr, fq);
.LBB0_588:
	s_cmpk_lg_i32 s60, 0x400
	s_cbranch_scc1 .LBB0_587
	v_mov_b32_e32 v4, v1
	v_mov_b32_e32 v3, v208
	s_nop 0
	v_ashrrev_i32_e32 v5, 31, v4
	v_lshlrev_b32_e32 v134, 3, v3
	v_lshl_add_u64 v[4:5], v[4:5], 0, s[20:21]
	v_ashrrev_i32_e32 v135, 31, v134
	v_lshlrev_b64 v[4:5], 11, v[4:5]
	v_lshl_add_u64 v[134:135], v[134:135], 1, s[48:49]
	v_lshl_add_u64 v[4:5], v[134:135], 0, v[4:5]
	global_load_dwordx4 v[212:215], v[4:5], off nt
	global_load_dwordx4 v[216:219], v[4:5], off offset:256 nt
	v_add_co_u32_e32 v134, vcc, s75, v4
	s_nop 1
	v_addc_co_u32_e32 v135, vcc, 0, v5, vcc
	global_load_dwordx4 v[186:189], v[134:135], off nt
	global_load_dwordx4 v[182:185], v[134:135], off offset:256 nt
	v_add_co_u32_e32 v134, vcc, s69, v4
	s_nop 1
	v_addc_co_u32_e32 v135, vcc, 0, v5, vcc
	global_load_dwordx4 v[178:181], v[134:135], off nt
	global_load_dwordx4 v[174:177], v[134:135], off offset:256 nt
	v_add_co_u32_e32 v134, vcc, s74, v4
	s_nop 1
	v_addc_co_u32_e32 v135, vcc, 0, v5, vcc
	global_load_dwordx4 v[170:173], v[134:135], off nt
	global_load_dwordx4 v[166:169], v[134:135], off offset:256 nt
	v_add_co_u32_e32 v134, vcc, s84, v4
	s_nop 1
	v_addc_co_u32_e32 v135, vcc, 0, v5, vcc
	global_load_dwordx4 v[162:165], v[134:135], off nt
	global_load_dwordx4 v[158:161], v[134:135], off offset:256 nt
	v_add_co_u32_e32 v134, vcc, s85, v4
	s_nop 1
	v_addc_co_u32_e32 v135, vcc, 0, v5, vcc
	global_load_dwordx4 v[154:157], v[134:135], off nt
	global_load_dwordx4 v[150:153], v[134:135], off offset:256 nt
	v_add_co_u32_e32 v134, vcc, s86, v4
	s_nop 1
	v_addc_co_u32_e32 v135, vcc, 0, v5, vcc
	global_load_dwordx4 v[146:149], v[134:135], off nt
	global_load_dwordx4 v[138:141], v[134:135], off offset:256 nt
	v_add_co_u32_e32 v4, vcc, s87, v4
	s_nop 1
	v_addc_co_u32_e32 v5, vcc, 0, v5, vcc
	global_load_dwordx4 v[142:145], v[4:5], off nt
	global_load_dwordx4 v[134:137], v[4:5], off offset:256 nt
	s_waitcnt vmcnt(15)
	v_lshlrev_b32_e32 v4, 16, v212
	v_and_b32_e32 v5, 0xffff0000, v212
	v_pk_mul_f32 v[130:131], v[130:131], v[4:5]
	v_lshlrev_b32_e32 v4, 16, v214
	v_and_b32_e32 v5, 0xffff0000, v214
	v_pk_mul_f32 v[126:127], v[126:127], v[4:5]
	s_waitcnt vmcnt(14)
	v_lshlrev_b32_e32 v4, 16, v216
	v_and_b32_e32 v5, 0xffff0000, v216
	v_pk_mul_f32 v[122:123], v[122:123], v[4:5]
	v_lshlrev_b32_e32 v4, 16, v218
	v_and_b32_e32 v5, 0xffff0000, v218
	v_pk_mul_f32 v[118:119], v[118:119], v[4:5]
	s_waitcnt vmcnt(13)
	v_lshlrev_b32_e32 v4, 16, v186
	v_and_b32_e32 v5, 0xffff0000, v186
	v_pk_mul_f32 v[114:115], v[114:115], v[4:5]
	v_lshlrev_b32_e32 v4, 16, v188
	v_and_b32_e32 v5, 0xffff0000, v188
	v_pk_mul_f32 v[110:111], v[110:111], v[4:5]
	s_waitcnt vmcnt(12)
	v_lshlrev_b32_e32 v4, 16, v182
	v_and_b32_e32 v5, 0xffff0000, v182
	v_pk_mul_f32 v[106:107], v[106:107], v[4:5]
	v_lshlrev_b32_e32 v4, 16, v184
	v_and_b32_e32 v5, 0xffff0000, v184
	v_pk_mul_f32 v[102:103], v[102:103], v[4:5]
	s_waitcnt vmcnt(11)
	v_lshlrev_b32_e32 v4, 16, v178
	v_and_b32_e32 v5, 0xffff0000, v178
	v_pk_mul_f32 v[98:99], v[98:99], v[4:5]
	v_lshlrev_b32_e32 v4, 16, v180
	v_and_b32_e32 v5, 0xffff0000, v180
	v_pk_mul_f32 v[94:95], v[94:95], v[4:5]
	s_waitcnt vmcnt(10)
	v_lshlrev_b32_e32 v4, 16, v174
	v_and_b32_e32 v5, 0xffff0000, v174
	v_pk_mul_f32 v[90:91], v[90:91], v[4:5]
	v_lshlrev_b32_e32 v4, 16, v176
	v_and_b32_e32 v5, 0xffff0000, v176
	v_pk_mul_f32 v[86:87], v[86:87], v[4:5]
	s_waitcnt vmcnt(9)
	v_lshlrev_b32_e32 v4, 16, v170
	v_and_b32_e32 v5, 0xffff0000, v170
	v_pk_mul_f32 v[82:83], v[82:83], v[4:5]
	v_lshlrev_b32_e32 v4, 16, v172
	v_and_b32_e32 v5, 0xffff0000, v172
	v_pk_mul_f32 v[78:79], v[78:79], v[4:5]
	s_waitcnt vmcnt(8)
	v_lshlrev_b32_e32 v4, 16, v166
	v_and_b32_e32 v5, 0xffff0000, v166
	v_pk_mul_f32 v[74:75], v[74:75], v[4:5]
	v_lshlrev_b32_e32 v4, 16, v168
	v_and_b32_e32 v5, 0xffff0000, v168
	v_pk_mul_f32 v[70:71], v[70:71], v[4:5]
	s_waitcnt vmcnt(7)
	v_lshlrev_b32_e32 v4, 16, v162
	v_and_b32_e32 v5, 0xffff0000, v162
	v_pk_mul_f32 v[66:67], v[66:67], v[4:5]
	v_lshlrev_b32_e32 v4, 16, v164
	v_and_b32_e32 v5, 0xffff0000, v164
	v_pk_mul_f32 v[62:63], v[62:63], v[4:5]
	s_waitcnt vmcnt(6)
	v_lshlrev_b32_e32 v4, 16, v158
	v_and_b32_e32 v5, 0xffff0000, v158
	v_pk_mul_f32 v[58:59], v[58:59], v[4:5]
	v_lshlrev_b32_e32 v4, 16, v160
	v_and_b32_e32 v5, 0xffff0000, v160
	v_pk_mul_f32 v[54:55], v[54:55], v[4:5]
	s_waitcnt vmcnt(5)
	v_lshlrev_b32_e32 v4, 16, v154
	v_and_b32_e32 v5, 0xffff0000, v154
	v_pk_mul_f32 v[50:51], v[50:51], v[4:5]
	v_lshlrev_b32_e32 v4, 16, v156
	v_and_b32_e32 v5, 0xffff0000, v156
	v_pk_mul_f32 v[46:47], v[46:47], v[4:5]
	s_waitcnt vmcnt(4)
	v_lshlrev_b32_e32 v4, 16, v150
	v_and_b32_e32 v5, 0xffff0000, v150
	v_pk_mul_f32 v[42:43], v[42:43], v[4:5]
	v_lshlrev_b32_e32 v4, 16, v152
	v_and_b32_e32 v5, 0xffff0000, v152
	v_pk_mul_f32 v[38:39], v[38:39], v[4:5]
	s_waitcnt vmcnt(3)
;     __device__ __forceinline__ void scale(f32x4 (&acc)[2][2][4][2], const bf16_t* G, const Unit& u, int wr, int wc, int fr, int fq) const {
;     ...
;         for (int ai = 0; ai < 2; ++ai)
; #pragma unroll
;             for (int m = 0; m < 4; ++m)
; #pragma unroll
;                 for (int bj = 0; bj < 2; ++bj) { const u32x4 a = gv[ai][m][bj];
;                     acc[ai][bj][m][0] *= (f32x4){bflo(a.x), bfhi(a.x), bflo(a.y), bfhi(a.y)}; acc[ai][bj][m][1] *= (f32x4){bflo(a.z), bfhi(a.z), bflo(a.w), bfhi(a.w)}; }
	v_lshlrev_b32_e32 v4, 16, v146
	v_and_b32_e32 v5, 0xffff0000, v146
	v_pk_mul_f32 v[34:35], v[34:35], v[4:5]
	v_lshlrev_b32_e32 v4, 16, v148
	v_and_b32_e32 v5, 0xffff0000, v148
	v_pk_mul_f32 v[30:31], v[30:31], v[4:5]
	s_waitcnt vmcnt(2)
	v_lshlrev_b32_e32 v4, 16, v138
	v_and_b32_e32 v5, 0xffff0000, v138
	v_pk_mul_f32 v[26:27], v[26:27], v[4:5]
	v_lshlrev_b32_e32 v4, 16, v140
	v_and_b32_e32 v5, 0xffff0000, v140
	v_lshlrev_b32_e32 v212, 16, v213
	v_and_b32_e32 v213, 0xffff0000, v213
	v_lshlrev_b32_e32 v138, 16, v139
	v_and_b32_e32 v139, 0xffff0000, v139
	v_pk_mul_f32 v[22:23], v[22:23], v[4:5]
	s_waitcnt vmcnt(1)
	v_lshlrev_b32_e32 v4, 16, v142
	v_and_b32_e32 v5, 0xffff0000, v142
	v_pk_mul_f32 v[132:133], v[132:133], v[212:213]
	v_lshlrev_b32_e32 v212, 16, v215
	v_and_b32_e32 v213, 0xffff0000, v215
	v_pk_mul_f32 v[28:29], v[28:29], v[138:139]
	v_lshlrev_b32_e32 v138, 16, v141
	v_and_b32_e32 v139, 0xffff0000, v141
	v_pk_mul_f32 v[18:19], v[18:19], v[4:5]
	v_lshlrev_b32_e32 v4, 16, v144
	v_and_b32_e32 v5, 0xffff0000, v144
	v_pk_mul_f32 v[128:129], v[128:129], v[212:213]
	v_lshlrev_b32_e32 v212, 16, v217
	v_and_b32_e32 v213, 0xffff0000, v217
	v_lshlrev_b32_e32 v186, 16, v187
	v_and_b32_e32 v187, 0xffff0000, v187
	v_lshlrev_b32_e32 v182, 16, v183
	v_and_b32_e32 v183, 0xffff0000, v183
	v_lshlrev_b32_e32 v178, 16, v179
	v_and_b32_e32 v179, 0xffff0000, v179
	v_lshlrev_b32_e32 v174, 16, v175
	v_and_b32_e32 v175, 0xffff0000, v175
	v_lshlrev_b32_e32 v170, 16, v171
	v_and_b32_e32 v171, 0xffff0000, v171
	v_lshlrev_b32_e32 v166, 16, v167
	v_and_b32_e32 v167, 0xffff0000, v167
	v_lshlrev_b32_e32 v162, 16, v163
	v_and_b32_e32 v163, 0xffff0000, v163
	v_lshlrev_b32_e32 v158, 16, v159
	v_and_b32_e32 v159, 0xffff0000, v159
	v_lshlrev_b32_e32 v154, 16, v155
	v_and_b32_e32 v155, 0xffff0000, v155
	v_lshlrev_b32_e32 v150, 16, v151
	v_and_b32_e32 v151, 0xffff0000, v151
	v_lshlrev_b32_e32 v146, 16, v147
	v_and_b32_e32 v147, 0xffff0000, v147
	v_pk_mul_f32 v[24:25], v[24:25], v[138:139]
	v_lshlrev_b32_e32 v138, 16, v143
	v_and_b32_e32 v139, 0xffff0000, v143
	v_pk_mul_f32 v[14:15], v[14:15], v[4:5]
	s_waitcnt vmcnt(0)
	v_lshlrev_b32_e32 v4, 16, v134
	v_and_b32_e32 v5, 0xffff0000, v134
	v_lshlrev_b32_e32 v134, 16, v135
	v_and_b32_e32 v135, 0xffff0000, v135
	v_pk_mul_f32 v[124:125], v[124:125], v[212:213]
	v_lshlrev_b32_e32 v212, 16, v219
	v_and_b32_e32 v213, 0xffff0000, v219
	v_pk_mul_f32 v[116:117], v[116:117], v[186:187]
	v_lshlrev_b32_e32 v186, 16, v189
	v_and_b32_e32 v187, 0xffff0000, v189
	v_pk_mul_f32 v[108:109], v[108:109], v[182:183]
	v_lshlrev_b32_e32 v182, 16, v185
	v_and_b32_e32 v183, 0xffff0000, v185
	v_pk_mul_f32 v[100:101], v[100:101], v[178:179]
	v_lshlrev_b32_e32 v178, 16, v181
	v_and_b32_e32 v179, 0xffff0000, v181
	v_pk_mul_f32 v[92:93], v[92:93], v[174:175]
	v_lshlrev_b32_e32 v174, 16, v177
	v_and_b32_e32 v175, 0xffff0000, v177
	v_pk_mul_f32 v[84:85], v[84:85], v[170:171]
	v_lshlrev_b32_e32 v170, 16, v173
	v_and_b32_e32 v171, 0xffff0000, v173
	v_pk_mul_f32 v[76:77], v[76:77], v[166:167]
	v_lshlrev_b32_e32 v166, 16, v169
	v_and_b32_e32 v167, 0xffff0000, v169
	v_pk_mul_f32 v[68:69], v[68:69], v[162:163]
	v_lshlrev_b32_e32 v162, 16, v165
	v_and_b32_e32 v163, 0xffff0000, v165
	v_pk_mul_f32 v[60:61], v[60:61], v[158:159]
	v_lshlrev_b32_e32 v158, 16, v161
	v_and_b32_e32 v159, 0xffff0000, v161
	v_pk_mul_f32 v[52:53], v[52:53], v[154:155]
	v_lshlrev_b32_e32 v154, 16, v157
	v_and_b32_e32 v155, 0xffff0000, v157
	v_pk_mul_f32 v[44:45], v[44:45], v[150:151]
	v_lshlrev_b32_e32 v150, 16, v153
	v_and_b32_e32 v151, 0xffff0000, v153
	v_pk_mul_f32 v[36:37], v[36:37], v[146:147]
	v_lshlrev_b32_e32 v146, 16, v149
	v_and_b32_e32 v147, 0xffff0000, v149
	v_pk_mul_f32 v[20:21], v[20:21], v[138:139]
	v_lshlrev_b32_e32 v138, 16, v145
	v_and_b32_e32 v139, 0xffff0000, v145
	v_pk_mul_f32 v[12:13], v[12:13], v[134:135]
	v_pk_mul_f32 v[10:11], v[10:11], v[4:5]
	v_lshlrev_b32_e32 v4, 16, v136
	v_and_b32_e32 v5, 0xffff0000, v136
	v_lshlrev_b32_e32 v134, 16, v137
	v_and_b32_e32 v135, 0xffff0000, v137
	v_pk_mul_f32 v[120:121], v[120:121], v[212:213]
	v_pk_mul_f32 v[112:113], v[112:113], v[186:187]
	v_pk_mul_f32 v[104:105], v[104:105], v[182:183]
	v_pk_mul_f32 v[96:97], v[96:97], v[178:179]
	v_pk_mul_f32 v[88:89], v[88:89], v[174:175]
	v_pk_mul_f32 v[80:81], v[80:81], v[170:171]
	v_pk_mul_f32 v[72:73], v[72:73], v[166:167]
	v_pk_mul_f32 v[64:65], v[64:65], v[162:163]
	v_pk_mul_f32 v[56:57], v[56:57], v[158:159]
	v_pk_mul_f32 v[48:49], v[48:49], v[154:155]
	v_pk_mul_f32 v[40:41], v[40:41], v[150:151]
	v_pk_mul_f32 v[32:33], v[32:33], v[146:147]
	v_pk_mul_f32 v[16:17], v[16:17], v[138:139]
	v_pk_mul_f32 v[8:9], v[8:9], v[134:135]
	v_pk_mul_f32 v[6:7], v[6:7], v[4:5]
	s_branch .LBB0_587

;     __device__ __forceinline__ void scale(f32x4 (&acc)[2][2][4][2], const bf16_t* G, const Unit& u, int wr, int wc, int fr, int fq) const {
;         u32x4 gv[2][4][2];
; #pragma unroll
;         for (int ai = 0; ai < 2; ++ai)
; #pragma unroll
;             for (int m = 0; m < 4; ++m) { const size_t row = (size_t)u.pm * 256 + 128 * ai + 64 * wr + 16 * m + fr;
; #pragma unroll
;                 for (int bj = 0; bj < 2; ++bj) gv[ai][m][bj] = __builtin_nontemporal_load((const u32x4*)(G + row * DM + u.pn * 256 + 128 * bj + 32 * wc + 8 * fq)); }
; #pragma unroll
;         for (int ai = 0; ai < 2; ++ai)
; #pragma unroll
;             for (int m = 0; m < 4; ++m)
; #pragma unroll
;                 for (int bj = 0; bj < 2; ++bj) { const u32x4 a = gv[ai][m][bj];
;                     acc[ai][bj][m][0] *= (f32x4){bflo(a.x), bfhi(a.x), bflo(a.y), bfhi(a.y)}; acc[ai][bj][m][1] *= (f32x4){bflo(a.z), bfhi(a.z), bflo(a.w), bfhi(a.w)}; }
;     __device__ __forceinline__ void operator()(f32x4 (&acc)[2][2][4][2], const Unit& u, int wr, int wc, int fr, int fq) const {
;     ...
;         scale(acc, G1, u, wr, wc, fr, fq);
.LBB0_592:
	v_mov_b32_e32 v4, v1
	v_mov_b32_e32 v3, v208
	v_ashrrev_i32_e32 v5, 31, v4
	v_lshl_add_u64 v[134:135], v[4:5], 0, s[20:21]
	v_lshlrev_b32_e32 v4, 3, v3
	s_add_u32 s46, s78, s42
	v_ashrrev_i32_e32 v5, 31, v4
	s_addc_u32 s47, s79, s43
	v_lshlrev_b64 v[4:5], 1, v[4:5]
	v_lshl_add_u64 v[136:137], s[46:47], 0, v[4:5]
	v_lshlrev_b64 v[158:159], 11, v[134:135]
	v_lshl_add_u64 v[134:135], v[136:137], 0, s[44:45]
	v_lshl_add_u64 v[134:135], v[134:135], 0, v[158:159]
	v_add_co_u32_e32 v136, vcc, s75, v134
	global_load_dwordx4 v[160:163], v[134:135], off nt
	global_load_dwordx4 v[164:167], v[134:135], off offset:256 nt
	v_addc_co_u32_e32 v137, vcc, 0, v135, vcc
	global_load_dwordx4 v[168:171], v[136:137], off nt
	global_load_dwordx4 v[172:175], v[136:137], off offset:256 nt
	v_add_co_u32_e32 v136, vcc, s69, v134
	s_add_u32 s44, s70, s44
	s_nop 0
	v_addc_co_u32_e32 v137, vcc, 0, v135, vcc
	global_load_dwordx4 v[176:179], v[136:137], off nt
	global_load_dwordx4 v[180:183], v[136:137], off offset:256 nt
	v_add_co_u32_e32 v138, vcc, s74, v134
	s_addc_u32 s45, s71, s45
	s_nop 0
	v_addc_co_u32_e32 v139, vcc, 0, v135, vcc
	v_add_co_u32_e32 v140, vcc, s84, v134
	s_nop 1
	v_addc_co_u32_e32 v141, vcc, 0, v135, vcc
	v_add_co_u32_e32 v136, vcc, s85, v134
	s_nop 1
	v_addc_co_u32_e32 v137, vcc, 0, v135, vcc
	v_add_co_u32_e32 v142, vcc, s86, v134
	s_nop 1
	v_addc_co_u32_e32 v143, vcc, 0, v135, vcc
	v_add_co_u32_e32 v134, vcc, s87, v134
	s_nop 1
	v_addc_co_u32_e32 v135, vcc, 0, v135, vcc
	global_load_dwordx4 v[184:187], v[138:139], off nt
	global_load_dwordx4 v[204:207], v[138:139], off offset:256 nt
	global_load_dwordx4 v[212:215], v[140:141], off nt
	global_load_dwordx4 v[216:219], v[140:141], off offset:256 nt
	global_load_dwordx4 v[154:157], v[136:137], off nt
	global_load_dwordx4 v[150:153], v[136:137], off offset:256 nt
	global_load_dwordx4 v[146:149], v[142:143], off nt
	s_nop 0
	global_load_dwordx4 v[142:145], v[142:143], off offset:256 nt
	s_nop 0
	global_load_dwordx4 v[138:141], v[134:135], off nt
	s_nop 0
	global_load_dwordx4 v[134:137], v[134:135], off offset:256 nt
	s_waitcnt vmcnt(10)
	v_lshlrev_b32_e32 v188, 16, v160
	v_and_b32_e32 v189, 0xffff0000, v160
	v_lshlrev_b32_e32 v160, 16, v161
	v_and_b32_e32 v161, 0xffff0000, v161
	v_pk_mul_f32 v[132:133], v[132:133], v[160:161]
	v_lshlrev_b32_e32 v160, 16, v168
	v_and_b32_e32 v161, 0xffff0000, v168
	v_pk_mul_f32 v[114:115], v[114:115], v[160:161]
	v_lshlrev_b32_e32 v160, 16, v171
	v_and_b32_e32 v161, 0xffff0000, v171
	v_pk_mul_f32 v[112:113], v[112:113], v[160:161]
	v_lshlrev_b32_e32 v160, 16, v172
	v_and_b32_e32 v161, 0xffff0000, v172
	v_pk_mul_f32 v[106:107], v[106:107], v[160:161]
	v_lshlrev_b32_e32 v160, 16, v174
	v_and_b32_e32 v161, 0xffff0000, v174
	v_pk_mul_f32 v[102:103], v[102:103], v[160:161]
	v_lshlrev_b32_e32 v160, 16, v176
	v_and_b32_e32 v161, 0xffff0000, v176
	v_pk_mul_f32 v[98:99], v[98:99], v[160:161]
	v_lshlrev_b32_e32 v160, 16, v178
	v_and_b32_e32 v161, 0xffff0000, v178
	v_pk_mul_f32 v[94:95], v[94:95], v[160:161]
	v_lshlrev_b32_e32 v160, 16, v180
	v_and_b32_e32 v161, 0xffff0000, v180
	v_pk_mul_f32 v[90:91], v[90:91], v[160:161]
	v_lshlrev_b32_e32 v160, 16, v182
	v_and_b32_e32 v161, 0xffff0000, v182
	v_pk_mul_f32 v[86:87], v[86:87], v[160:161]
	v_lshlrev_b32_e32 v220, 16, v162
	v_and_b32_e32 v221, 0xffff0000, v162
	v_lshlrev_b32_e32 v162, 16, v163
	v_and_b32_e32 v163, 0xffff0000, v163
	v_pk_mul_f32 v[126:127], v[126:127], v[220:221]
	v_pk_mul_f32 v[128:129], v[128:129], v[162:163]
	v_lshlrev_b32_e32 v162, 16, v169
	v_and_b32_e32 v163, 0xffff0000, v169
	v_pk_mul_f32 v[116:117], v[116:117], v[162:163]
	v_lshlrev_b32_e32 v162, 16, v173
	v_and_b32_e32 v163, 0xffff0000, v173
	v_lshlrev_b32_e32 v222, 16, v164
	v_and_b32_e32 v223, 0xffff0000, v164
	v_lshlrev_b32_e32 v164, 16, v165
	v_and_b32_e32 v165, 0xffff0000, v165
	v_lshlrev_b32_e32 v224, 16, v166
	v_and_b32_e32 v225, 0xffff0000, v166
	v_lshlrev_b32_e32 v166, 16, v167
	v_and_b32_e32 v167, 0xffff0000, v167
	v_pk_mul_f32 v[130:131], v[130:131], v[188:189]
	v_pk_mul_f32 v[108:109], v[108:109], v[162:163]
	v_lshlrev_b32_e32 v162, 16, v175
	v_and_b32_e32 v163, 0xffff0000, v175
	v_pk_mul_f32 v[124:125], v[124:125], v[164:165]
	v_pk_mul_f32 v[122:123], v[122:123], v[222:223]
	v_pk_mul_f32 v[120:121], v[120:121], v[166:167]
	v_pk_mul_f32 v[118:119], v[118:119], v[224:225]
	v_lshlrev_b32_e32 v164, 16, v170
	v_and_b32_e32 v165, 0xffff0000, v170
	v_pk_mul_f32 v[104:105], v[104:105], v[162:163]
	v_lshlrev_b32_e32 v162, 16, v177
	v_and_b32_e32 v163, 0xffff0000, v177
	v_pk_mul_f32 v[110:111], v[110:111], v[164:165]
	v_pk_mul_f32 v[100:101], v[100:101], v[162:163]
	v_lshlrev_b32_e32 v162, 16, v179
	v_and_b32_e32 v163, 0xffff0000, v179
	v_pk_mul_f32 v[96:97], v[96:97], v[162:163]
	v_lshlrev_b32_e32 v162, 16, v181
	v_and_b32_e32 v163, 0xffff0000, v181
	v_pk_mul_f32 v[92:93], v[92:93], v[162:163]
	v_lshlrev_b32_e32 v162, 16, v183
	v_and_b32_e32 v163, 0xffff0000, v183
	v_pk_mul_f32 v[88:89], v[88:89], v[162:163]
	s_waitcnt vmcnt(9)
	v_lshlrev_b32_e32 v160, 16, v184
	v_and_b32_e32 v161, 0xffff0000, v184
	v_pk_mul_f32 v[82:83], v[82:83], v[160:161]
	v_lshlrev_b32_e32 v160, 16, v186
	v_and_b32_e32 v161, 0xffff0000, v186
	v_pk_mul_f32 v[78:79], v[78:79], v[160:161]
	s_waitcnt vmcnt(8)
	v_lshlrev_b32_e32 v160, 16, v204
	v_and_b32_e32 v161, 0xffff0000, v204
	v_pk_mul_f32 v[74:75], v[74:75], v[160:161]
	v_lshlrev_b32_e32 v160, 16, v206
	v_and_b32_e32 v161, 0xffff0000, v206
	v_pk_mul_f32 v[70:71], v[70:71], v[160:161]
	s_waitcnt vmcnt(7)
;     __device__ __forceinline__ void scale(f32x4 (&acc)[2][2][4][2], const bf16_t* G, const Unit& u, int wr, int wc, int fr, int fq) const {
;     ...
;         for (int ai = 0; ai < 2; ++ai)
; #pragma unroll
;             for (int m = 0; m < 4; ++m)
; #pragma unroll
;                 for (int bj = 0; bj < 2; ++bj) { const u32x4 a = gv[ai][m][bj];
;                     acc[ai][bj][m][0] *= (f32x4){bflo(a.x), bfhi(a.x), bflo(a.y), bfhi(a.y)}; acc[ai][bj][m][1] *= (f32x4){bflo(a.z), bfhi(a.z), bflo(a.w), bfhi(a.w)}; }
	v_lshlrev_b32_e32 v160, 16, v212
	v_and_b32_e32 v161, 0xffff0000, v212
	v_pk_mul_f32 v[66:67], v[66:67], v[160:161]
	v_lshlrev_b32_e32 v160, 16, v214
	v_and_b32_e32 v161, 0xffff0000, v214
	v_pk_mul_f32 v[62:63], v[62:63], v[160:161]
	s_waitcnt vmcnt(6)
	v_lshlrev_b32_e32 v160, 16, v216
	v_and_b32_e32 v161, 0xffff0000, v216
	v_pk_mul_f32 v[58:59], v[58:59], v[160:161]
	v_lshlrev_b32_e32 v160, 16, v218
	v_and_b32_e32 v161, 0xffff0000, v218
	v_pk_mul_f32 v[54:55], v[54:55], v[160:161]
	s_waitcnt vmcnt(5)
	v_lshlrev_b32_e32 v160, 16, v154
	v_and_b32_e32 v161, 0xffff0000, v154
	v_lshlrev_b32_e32 v154, 16, v155
	v_and_b32_e32 v155, 0xffff0000, v155
	v_pk_mul_f32 v[52:53], v[52:53], v[154:155]
	v_lshlrev_b32_e32 v154, 16, v156
	v_and_b32_e32 v155, 0xffff0000, v156
	v_pk_mul_f32 v[46:47], v[46:47], v[154:155]
	s_waitcnt vmcnt(4)
	v_lshlrev_b32_e32 v154, 16, v150
	v_and_b32_e32 v155, 0xffff0000, v150
	v_lshlrev_b32_e32 v150, 16, v151
	v_and_b32_e32 v151, 0xffff0000, v151
	v_pk_mul_f32 v[44:45], v[44:45], v[150:151]
	v_lshlrev_b32_e32 v150, 16, v152
	v_and_b32_e32 v151, 0xffff0000, v152
	v_pk_mul_f32 v[38:39], v[38:39], v[150:151]
	s_waitcnt vmcnt(3)
	v_lshlrev_b32_e32 v150, 16, v146
	v_and_b32_e32 v151, 0xffff0000, v146
	v_lshlrev_b32_e32 v146, 16, v147
	v_and_b32_e32 v147, 0xffff0000, v147
	v_pk_mul_f32 v[36:37], v[36:37], v[146:147]
	v_lshlrev_b32_e32 v146, 16, v148
	v_and_b32_e32 v147, 0xffff0000, v148
	v_pk_mul_f32 v[30:31], v[30:31], v[146:147]
	s_waitcnt vmcnt(2)
	v_lshlrev_b32_e32 v146, 16, v142
	v_and_b32_e32 v147, 0xffff0000, v142
	v_lshlrev_b32_e32 v142, 16, v143
	v_and_b32_e32 v143, 0xffff0000, v143
	v_pk_mul_f32 v[28:29], v[28:29], v[142:143]
	v_lshlrev_b32_e32 v142, 16, v144
	v_and_b32_e32 v143, 0xffff0000, v144
	v_pk_mul_f32 v[22:23], v[22:23], v[142:143]
	s_waitcnt vmcnt(1)
	v_lshlrev_b32_e32 v142, 16, v138
	v_and_b32_e32 v143, 0xffff0000, v138
	v_lshlrev_b32_e32 v138, 16, v139
	v_and_b32_e32 v139, 0xffff0000, v139
	v_pk_mul_f32 v[20:21], v[20:21], v[138:139]
	v_lshlrev_b32_e32 v138, 16, v140
	v_and_b32_e32 v139, 0xffff0000, v140
	v_pk_mul_f32 v[14:15], v[14:15], v[138:139]
	s_waitcnt vmcnt(0)
; __device__ __forceinline__ u32x4 pack8f(const f32x4 a, const f32x4 b) { u32x4 w; w.x = cvt_pk_bf16(a[0], a[1]); w.y = cvt_pk_bf16(a[2], a[3]); w.z = cvt_pk_bf16(b[0], b[1]); w.w = cvt_pk_bf16(b[2], b[3]); return w; }
;     __device__ __forceinline__ void scale(f32x4 (&acc)[2][2][4][2], const bf16_t* G, const Unit& u, int wr, int wc, int fr, int fq) const {
;     ...
; #pragma unroll
;         for (int ai = 0; ai < 2; ++ai)
; #pragma unroll
;             for (int m = 0; m < 4; ++m)
; #pragma unroll
;                 for (int bj = 0; bj < 2; ++bj) { const u32x4 a = gv[ai][m][bj];
;                     acc[ai][bj][m][0] *= (f32x4){bflo(a.x), bfhi(a.x), bflo(a.y), bfhi(a.y)}; acc[ai][bj][m][1] *= (f32x4){bflo(a.z), bfhi(a.z), bflo(a.w), bfhi(a.w)}; }
;     }
;     __device__ __forceinline__ void mid(f32x4 (&acc)[2][2][4][2], const Unit& u, int wr, int wc, int fr, int fq) const {
;         asm volatile("" : "+v"(fr)); asm volatile("" : "+v"(fq));
;     ...
;         const unsigned long long t0_ = __builtin_amdgcn_s_memtime();
;     ...
;         scale(acc, RT, u, wr, wc, fr, fq);
;     ...
;         asm volatile("" : "+v"(acc[0][0][0][0])); if (blockIdx.x == 0 && threadIdx.x == 0) *this->wc += __builtin_amdgcn_s_memtime() - t0_;
;     ...
;     }
;     __device__ __forceinline__ void operator()(f32x4 (&acc)[2][2][4][2], const Unit& u, int wr, int wc, int fr, int fq) const {
;         asm volatile("" : "+v"(fr)); asm volatile("" : "+v"(fq));
;         scale(acc, G1, u, wr, wc, fr, fq);
; #pragma unroll
;         for (int ai = 0; ai < 2; ++ai)
; #pragma unroll
;             for (int m = 0; m < 4; ++m) { const size_t row = (size_t)u.pm * 256 + 128 * ai + 64 * wr + 16 * m + fr;
; #pragma unroll
;                 for (int bj = 0; bj < 2; ++bj) *(u32x4*)(MG + row * DM + u.pn * 256 + 128 * bj + 32 * wc + 8 * fq) = pack8f(acc[ai][bj][m][0], acc[ai][bj][m][1]); }
	v_lshlrev_b32_e32 v138, 16, v134
	v_and_b32_e32 v139, 0xffff0000, v134
	v_lshlrev_b32_e32 v134, 16, v135
	v_and_b32_e32 v135, 0xffff0000, v135
	v_pk_mul_f32 v[12:13], v[12:13], v[134:135]
	v_lshlrev_b32_e32 v134, 16, v136
	v_and_b32_e32 v135, 0xffff0000, v136
	v_lshlrev_b32_e32 v136, 16, v137
	v_and_b32_e32 v137, 0xffff0000, v137
	v_pk_mul_f32 v[136:137], v[8:9], v[136:137]
	v_cvt_pk_bf16_f32 v8, v126, v127
	v_lshl_add_u64 v[126:127], s[44:45], 0, v[158:159]
	v_lshl_add_u64 v[126:127], v[126:127], 0, s[42:43]
	v_lshl_add_u64 v[126:127], v[126:127], 0, s[10:11]
	v_pk_mul_f32 v[134:135], v[6:7], v[134:135]
	v_cvt_pk_bf16_f32 v6, v130, v131
	v_cvt_pk_bf16_f32 v7, v132, v133
	v_cvt_pk_bf16_f32 v9, v128, v129
	v_lshl_add_u64 v[126:127], v[126:127], 0, v[4:5]
	global_store_dwordx4 v[126:127], v[6:9], off
	v_cvt_pk_bf16_f32 v4, v122, v123
	v_cvt_pk_bf16_f32 v5, v124, v125
	v_cvt_pk_bf16_f32 v6, v118, v119
	v_cvt_pk_bf16_f32 v7, v120, v121
	global_store_dwordx4 v[126:127], v[4:7], off offset:256
	s_mov_b64 s[42:43], 0x8000
	v_lshlrev_b32_e32 v162, 16, v185
	v_cvt_pk_bf16_f32 v6, v110, v111
	v_add_co_u32_e32 v110, vcc, s75, v126
	v_cvt_pk_bf16_f32 v4, v114, v115
	v_cvt_pk_bf16_f32 v5, v116, v117
	v_cvt_pk_bf16_f32 v7, v112, v113
	v_addc_co_u32_e32 v111, vcc, 0, v127, vcc
	v_and_b32_e32 v163, 0xffff0000, v185
	v_lshl_add_u64 v[8:9], v[126:127], 0, s[42:43]
	global_store_dwordx4 v[110:111], v[4:7], off
	v_pk_mul_f32 v[84:85], v[84:85], v[162:163]
	v_lshlrev_b32_e32 v162, 16, v187
	v_cvt_pk_bf16_f32 v4, v106, v107
	v_cvt_pk_bf16_f32 v5, v108, v109
	v_cvt_pk_bf16_f32 v6, v102, v103
	v_cvt_pk_bf16_f32 v7, v104, v105
	v_and_b32_e32 v163, 0xffff0000, v187
	global_store_dwordx4 v[8:9], v[4:7], off offset:256
	v_pk_mul_f32 v[80:81], v[80:81], v[162:163]
	v_lshlrev_b32_e32 v162, 16, v205
	v_cvt_pk_bf16_f32 v6, v94, v95
	v_add_co_u32_e32 v94, vcc, s69, v126
	v_and_b32_e32 v163, 0xffff0000, v205
	v_cvt_pk_bf16_f32 v4, v98, v99
	v_cvt_pk_bf16_f32 v5, v100, v101
	v_cvt_pk_bf16_f32 v7, v96, v97
	s_mov_b64 s[42:43], 0x10000
	v_addc_co_u32_e32 v95, vcc, 0, v127, vcc
	v_pk_mul_f32 v[76:77], v[76:77], v[162:163]
	v_lshlrev_b32_e32 v162, 16, v207
	v_and_b32_e32 v163, 0xffff0000, v207
	v_lshl_add_u64 v[8:9], v[126:127], 0, s[42:43]
	global_store_dwordx4 v[94:95], v[4:7], off
	v_pk_mul_f32 v[72:73], v[72:73], v[162:163]
	v_lshlrev_b32_e32 v162, 16, v213
	v_cvt_pk_bf16_f32 v4, v90, v91
	v_cvt_pk_bf16_f32 v5, v92, v93
	v_cvt_pk_bf16_f32 v6, v86, v87
	v_cvt_pk_bf16_f32 v7, v88, v89
	v_and_b32_e32 v163, 0xffff0000, v213
	global_store_dwordx4 v[8:9], v[4:7], off offset:256
	v_pk_mul_f32 v[68:69], v[68:69], v[162:163]
	v_lshlrev_b32_e32 v162, 16, v215
	v_cvt_pk_bf16_f32 v6, v78, v79
	v_add_co_u32_e32 v78, vcc, s74, v126
	v_and_b32_e32 v163, 0xffff0000, v215
	v_cvt_pk_bf16_f32 v4, v82, v83
	v_cvt_pk_bf16_f32 v5, v84, v85
	v_cvt_pk_bf16_f32 v7, v80, v81
	s_mov_b64 s[42:43], 0x18000
	v_addc_co_u32_e32 v79, vcc, 0, v127, vcc
	v_pk_mul_f32 v[64:65], v[64:65], v[162:163]
	v_lshlrev_b32_e32 v162, 16, v217
	v_and_b32_e32 v163, 0xffff0000, v217
	v_lshl_add_u64 v[8:9], v[126:127], 0, s[42:43]
	global_store_dwordx4 v[78:79], v[4:7], off
	v_pk_mul_f32 v[60:61], v[60:61], v[162:163]
	v_lshlrev_b32_e32 v162, 16, v219
	v_cvt_pk_bf16_f32 v4, v74, v75
	v_cvt_pk_bf16_f32 v5, v76, v77
	v_cvt_pk_bf16_f32 v6, v70, v71
	v_cvt_pk_bf16_f32 v7, v72, v73
	v_and_b32_e32 v163, 0xffff0000, v219
	global_store_dwordx4 v[8:9], v[4:7], off offset:256
	v_pk_mul_f32 v[56:57], v[56:57], v[162:163]
	s_mov_b64 s[42:43], 0x40000
	v_cvt_pk_bf16_f32 v6, v62, v63
	v_add_co_u32_e32 v62, vcc, s84, v126
	v_cvt_pk_bf16_f32 v4, v66, v67
	v_cvt_pk_bf16_f32 v5, v68, v69
	v_cvt_pk_bf16_f32 v7, v64, v65
	v_addc_co_u32_e32 v63, vcc, 0, v127, vcc
	v_lshlrev_b32_e32 v156, 16, v157
	v_and_b32_e32 v157, 0xffff0000, v157
	v_lshl_add_u64 v[8:9], v[126:127], 0, s[42:43]
	global_store_dwordx4 v[62:63], v[4:7], off
	v_pk_mul_f32 v[50:51], v[50:51], v[160:161]
	v_pk_mul_f32 v[48:49], v[48:49], v[156:157]
	v_cvt_pk_bf16_f32 v4, v58, v59
	v_cvt_pk_bf16_f32 v5, v60, v61
	v_cvt_pk_bf16_f32 v6, v54, v55
	v_cvt_pk_bf16_f32 v7, v56, v57
	v_lshlrev_b32_e32 v152, 16, v153
	v_and_b32_e32 v153, 0xffff0000, v153
	global_store_dwordx4 v[8:9], v[4:7], off offset:256
	v_pk_mul_f32 v[42:43], v[42:43], v[154:155]
	v_pk_mul_f32 v[40:41], v[40:41], v[152:153]
	v_cvt_pk_bf16_f32 v6, v46, v47
	v_add_co_u32_e32 v46, vcc, s85, v126
	v_cvt_pk_bf16_f32 v4, v50, v51
	v_cvt_pk_bf16_f32 v5, v52, v53
	v_cvt_pk_bf16_f32 v7, v48, v49
	s_mov_b64 s[42:43], 0x48000
	v_addc_co_u32_e32 v47, vcc, 0, v127, vcc
	v_lshlrev_b32_e32 v148, 16, v149
	v_and_b32_e32 v149, 0xffff0000, v149
	v_lshl_add_u64 v[8:9], v[126:127], 0, s[42:43]
	global_store_dwordx4 v[46:47], v[4:7], off
	v_pk_mul_f32 v[34:35], v[34:35], v[150:151]
	v_pk_mul_f32 v[32:33], v[32:33], v[148:149]
	v_cvt_pk_bf16_f32 v4, v42, v43
	v_cvt_pk_bf16_f32 v5, v44, v45
	v_cvt_pk_bf16_f32 v6, v38, v39
	v_cvt_pk_bf16_f32 v7, v40, v41
	v_lshlrev_b32_e32 v144, 16, v145
	v_and_b32_e32 v145, 0xffff0000, v145
	global_store_dwordx4 v[8:9], v[4:7], off offset:256
	v_pk_mul_f32 v[26:27], v[26:27], v[146:147]
	v_pk_mul_f32 v[24:25], v[24:25], v[144:145]
	v_cvt_pk_bf16_f32 v6, v30, v31
	v_add_co_u32_e32 v30, vcc, s86, v126
	v_cvt_pk_bf16_f32 v4, v34, v35
	v_cvt_pk_bf16_f32 v5, v36, v37
	v_cvt_pk_bf16_f32 v7, v32, v33
	s_mov_b64 s[42:43], 0x50000
	v_addc_co_u32_e32 v31, vcc, 0, v127, vcc
	v_lshlrev_b32_e32 v140, 16, v141
	v_and_b32_e32 v141, 0xffff0000, v141
	v_lshl_add_u64 v[8:9], v[126:127], 0, s[42:43]
	global_store_dwordx4 v[30:31], v[4:7], off
	v_pk_mul_f32 v[18:19], v[18:19], v[142:143]
	v_pk_mul_f32 v[16:17], v[16:17], v[140:141]
	v_cvt_pk_bf16_f32 v4, v26, v27
	v_cvt_pk_bf16_f32 v5, v28, v29
	v_cvt_pk_bf16_f32 v6, v22, v23
	v_cvt_pk_bf16_f32 v7, v24, v25
	global_store_dwordx4 v[8:9], v[4:7], off offset:256
	v_pk_mul_f32 v[10:11], v[10:11], v[138:139]
	v_lshl_add_u64 v[8:9], v[126:127], 0, s[26:27]
	v_cvt_pk_bf16_f32 v6, v14, v15
	v_add_co_u32_e32 v14, vcc, s87, v126
	v_cvt_pk_bf16_f32 v4, v18, v19
	v_cvt_pk_bf16_f32 v5, v20, v21
	v_cvt_pk_bf16_f32 v7, v16, v17
	v_addc_co_u32_e32 v15, vcc, 0, v127, vcc
	global_store_dwordx4 v[14:15], v[4:7], off
	s_andn2_b64 vcc, exec, s[36:37]
	s_mov_b64 s[36:37], -1
	v_cvt_pk_bf16_f32 v4, v10, v11
	v_cvt_pk_bf16_f32 v5, v12, v13
	v_cvt_pk_bf16_f32 v6, v134, v135
	v_cvt_pk_bf16_f32 v7, v136, v137
	global_store_dwordx4 v[8:9], v[4:7], off offset:256
	s_cbranch_vccnz .LBB0_574
	s_andn2_b64 vcc, exec, s[18:19]
	s_cbranch_vccnz .LBB0_573
	s_barrier
	s_branch .LBB0_573
